# attention: one static s_setprio 1 for waves 4-7 before each flash unit's tile loop (reset at the unit epilogue), no per-segment flips
# baseline (speedup 1.0000x reference)
; __device__ __forceinline__ unsigned pk2(float lo, float hi) { const f32x2 v = {lo, hi}; return __builtin_bit_cast(unsigned, __builtin_convertvector(v, bf16x2_t)); }
; __device__ __forceinline__ float half_sum(float v) { auto rr = __builtin_amdgcn_permlane32_swap(__float_as_uint(v), __float_as_uint(v), false, false); return __uint_as_float(rr[0]) + __uint_as_float(rr[1]); }
; template <int DQK, int DV, int MODE>
; __device__ __forceinline__ void flash_unit(LAS unsigned char* lds, const bf16* Qp, int qpitch, const bf16* K0, int kpitch, const bf16* K1, const bf16* VT, int vpitch,
;                                            bf16* Op, int opitch, int NT, int jbase, int qpos0) {
;     ...
;     { const float lt = half_sum(lrun), inv = 1.f / lt;
;       bf16* orow = Op + (size_t)(wid * 32 + r32) * opitch + 4 * hi;
; #pragma unroll
;       for (int db = 0; db < NDB; ++db)
; #pragma unroll
;           for (int rg = 0; rg < 4; ++rg) { u32x2 w; w.x = pk2(o[db][4 * rg] * inv, o[db][4 * rg + 1] * inv); w.y = pk2(o[db][4 * rg + 2] * inv, o[db][4 * rg + 3] * inv);
;               *(u32x2*)(orow + 32 * db + 8 * rg) = w; } }
.LBB0_511:
	s_setprio 0
	v_mov_b32_e32 v0, v159
	s_nop 1
	v_permlane32_swap_b32_e32 v159, v0
	v_add_f32_e32 v0, v159, v0
	s_waitcnt vmcnt(0) lgkmcnt(0)
	v_div_scale_f32 v2, s[4:5], v0, v0, 1.0
	v_rcp_f32_e32 v3, v2
	s_lshl_b64 s[2:3], s[24:25], 11
	s_add_u32 s2, s61, s2
	s_addc_u32 s3, s62, s3
	v_fma_f32 v4, -v2, v3, 1.0
	v_fmac_f32_e32 v3, v4, v3
	v_div_scale_f32 v4, vcc, 1.0, v0, 1.0
	v_mul_f32_e32 v5, v4, v3
	v_fma_f32 v6, -v2, v5, v4
	v_fmac_f32_e32 v5, v6, v3
	v_fma_f32 v2, -v2, v5, v4
	v_div_fmas_f32 v2, v2, v3, v5
	v_div_fixup_f32 v0, v2, v0, 1.0
	v_lshlrev_b64 v[2:3], 11, v[152:153]
	v_lshl_add_u64 v[2:3], s[2:3], 0, v[2:3]
	v_mov_b32_e32 v155, v1
	v_pk_mul_f32 v[4:5], v[32:33], v[0:1] op_sel_hi:[1,0]
	v_pk_mul_f32 v[6:7], v[34:35], v[0:1] op_sel_hi:[1,0]
	v_lshl_add_u64 v[2:3], v[2:3], 0, v[154:155]
	v_cvt_pk_bf16_f32 v4, v4, v5
	v_cvt_pk_bf16_f32 v5, v6, v7
	s_barrier
	global_store_dwordx2 v[2:3], v[4:5], off
	v_pk_mul_f32 v[4:5], v[36:37], v[0:1] op_sel_hi:[1,0]
	v_pk_mul_f32 v[6:7], v[38:39], v[0:1] op_sel_hi:[1,0]
	v_cvt_pk_bf16_f32 v4, v4, v5
	v_cvt_pk_bf16_f32 v5, v6, v7
	global_store_dwordx2 v[2:3], v[4:5], off offset:16
	v_pk_mul_f32 v[4:5], v[40:41], v[0:1] op_sel_hi:[1,0]
	v_pk_mul_f32 v[6:7], v[42:43], v[0:1] op_sel_hi:[1,0]
	v_cvt_pk_bf16_f32 v4, v4, v5
	v_cvt_pk_bf16_f32 v5, v6, v7
	global_store_dwordx2 v[2:3], v[4:5], off offset:32
	v_pk_mul_f32 v[4:5], v[44:45], v[0:1] op_sel_hi:[1,0]
	v_pk_mul_f32 v[6:7], v[46:47], v[0:1] op_sel_hi:[1,0]
	v_cvt_pk_bf16_f32 v4, v4, v5
	v_cvt_pk_bf16_f32 v5, v6, v7
	global_store_dwordx2 v[2:3], v[4:5], off offset:48
	v_pk_mul_f32 v[4:5], v[16:17], v[0:1] op_sel_hi:[1,0]
	v_pk_mul_f32 v[6:7], v[18:19], v[0:1] op_sel_hi:[1,0]
	v_cvt_pk_bf16_f32 v4, v4, v5
	v_cvt_pk_bf16_f32 v5, v6, v7
	global_store_dwordx2 v[2:3], v[4:5], off offset:64
	v_pk_mul_f32 v[4:5], v[20:21], v[0:1] op_sel_hi:[1,0]
	v_pk_mul_f32 v[6:7], v[22:23], v[0:1] op_sel_hi:[1,0]
	v_cvt_pk_bf16_f32 v4, v4, v5
	v_cvt_pk_bf16_f32 v5, v6, v7
	global_store_dwordx2 v[2:3], v[4:5], off offset:80
	v_pk_mul_f32 v[4:5], v[24:25], v[0:1] op_sel_hi:[1,0]
	v_pk_mul_f32 v[6:7], v[26:27], v[0:1] op_sel_hi:[1,0]
	v_cvt_pk_bf16_f32 v4, v4, v5
	v_cvt_pk_bf16_f32 v5, v6, v7
	global_store_dwordx2 v[2:3], v[4:5], off offset:96
	v_pk_mul_f32 v[4:5], v[28:29], v[0:1] op_sel_hi:[1,0]
	v_pk_mul_f32 v[6:7], v[30:31], v[0:1] op_sel_hi:[1,0]
	v_cvt_pk_bf16_f32 v4, v4, v5
	v_cvt_pk_bf16_f32 v5, v6, v7
	s_mov_b64 s[4:5], 0
	s_and_b64 vcc, exec, s[22:23]
	global_store_dwordx2 v[2:3], v[4:5], off offset:112
	s_cbranch_vccnz .LBB0_508

; __device__ __forceinline__ float bflo(unsigned w) { return __uint_as_float(w << 16); }
; __device__ __forceinline__ float bfhi(unsigned w) { return __uint_as_float(w & 0xffff0000u); }
; __device__ __forceinline__ unsigned pk2(float lo, float hi) { const f32x2 v = {lo, hi}; return __builtin_bit_cast(unsigned, __builtin_convertvector(v, bf16x2_t)); }
; __device__ __forceinline__ float ex2f(float x) { return __builtin_amdgcn_exp2f(x); }
; template <int DQK, int DV, int MODE>
; __device__ __forceinline__ void flash_unit(LAS unsigned char* lds, const bf16* Qp, int qpitch, const bf16* K0, int kpitch, const bf16* K1, const bf16* VT, int vpitch,
;                                            bf16* Op, int opitch, int NT, int jbase, int qpos0) {
;     ...
;         const float pos = (float)(qpos0 + wid * 32 + r32);
;         const u32x4 xa = __builtin_bit_cast(u32x4, qf[ND0 - 2]), xb = __builtin_bit_cast(u32x4, qf[ND0 - 1]); u32x4 ra, rb;
; #pragma unroll
;         for (int e = 0; e < 4; ++e) { const float a0 = bflo(xa[e]), a1 = bfhi(xa[e]), b0 = bflo(xb[e]), b1 = bfhi(xb[e]);
;             float s0_, c0_, s1_, c1_; sincos_rev(pos * ex2f(-(float)(8 * hi + 2 * e) * (2.0f / 32.0f) * LG2_10000), s0_, c0_); sincos_rev(pos * ex2f(-(float)(8 * hi + 2 * e + 1) * (2.0f / 32.0f) * LG2_10000), s1_, c1_);
;             ra[e] = pk2(a0 * c0_ - b0 * s0_, a1 * c1_ - b1 * s1_); rb[e] = pk2(b0 * c0_ + a0 * s0_, b1 * c1_ + a1 * s1_); }
;         qf[ND0 - 2] = __builtin_bit_cast(bf16x8, ra); qf[ND0 - 1] = __builtin_bit_cast(bf16x8, rb);
.LBB0_540:
	s_or_b64 exec, exec, s[26:27]
	global_load_dwordx4 v[64:67], v[156:157], off offset:128
	v_or_b32_e32 v10, s8, v17
	v_add_u32_e32 v10, s66, v10
	v_cvt_f32_i32_e32 v20, v10
	v_cvt_f32_ubyte0_e32 v10, v154
	v_mul_f32_e32 v10, 0xbd800000, v10
	v_mul_f32_e32 v10, 0x41549a78, v10
	v_exp_f32_e32 v10, v10
	v_or_b32_e32 v11, 1, v154
	v_cvt_f32_ubyte0_e32 v11, v11
	v_mad_u32_u24 v0, v17, s51, v154
	v_mul_f32_e32 v11, 0xbd800000, v11
	v_lshl_add_u32 v169, v0, 1, 0
	v_mul_u32_u24_e32 v0, 0x88, v17
	v_mul_f32_e32 v11, 0x41549a78, v11
	v_add3_u32 v165, 0, v154, v0
	v_mul_f32_e32 v0, v10, v20
	v_exp_f32_e32 v11, v11
	v_mul_f32_e32 v10, 0.15915494, v0
	v_floor_f32_e32 v10, v10
	v_fma_f32 v0, v0, 0.15915494, -v10
	v_sin_f32_e32 v10, v0
	v_cos_f32_e32 v12, v0
	v_mul_f32_e32 v0, v11, v20
	v_mul_f32_e32 v11, 0.15915494, v0
	v_floor_f32_e32 v11, v11
	v_fma_f32 v0, v0, 0.15915494, -v11
	v_sin_f32_e32 v11, v0
	v_cos_f32_e32 v13, v0
	v_or_b32_e32 v0, 2, v154
	v_cvt_f32_ubyte0_e32 v0, v0
	v_mul_f32_e32 v0, 0xbd800000, v0
	v_mul_f32_e32 v0, 0x41549a78, v0
	v_lshlrev_b32_e32 v14, 16, v6
	v_and_b32_e32 v15, 0xffff0000, v6
	v_exp_f32_e32 v0, v0
	v_or_b32_e32 v6, 3, v154
	v_cvt_f32_ubyte0_e32 v6, v6
	v_mul_f32_e32 v6, 0xbd800000, v6
	v_mul_f32_e32 v6, 0x41549a78, v6
	v_mul_f32_e32 v0, v0, v20
	v_exp_f32_e32 v6, v6
	v_lshlrev_b32_e32 v16, 16, v2
	v_and_b32_e32 v17, 0xffff0000, v2
	v_mul_f32_e32 v2, 0.15915494, v0
	v_pk_mul_f32 v[18:19], v[10:11], v[16:17]
	v_pk_mul_f32 v[10:11], v[10:11], v[14:15]
	v_floor_f32_e32 v2, v2
	v_pk_fma_f32 v[10:11], v[12:13], v[16:17], v[10:11]
	v_fma_f32 v0, v0, 0.15915494, -v2
	v_pk_fma_f32 v[18:19], v[12:13], v[14:15], v[18:19] neg_lo:[0,0,1] neg_hi:[0,0,1]
	v_cvt_pk_bf16_f32 v124, v10, v11
	v_sin_f32_e32 v10, v0
	v_cos_f32_e32 v12, v0
	v_mul_f32_e32 v0, v6, v20
	v_mul_f32_e32 v2, 0.15915494, v0
	v_floor_f32_e32 v2, v2
	v_fma_f32 v0, v0, 0.15915494, -v2
	v_sin_f32_e32 v11, v0
	v_cos_f32_e32 v13, v0
	v_lshlrev_b32_e32 v2, 16, v3
	v_and_b32_e32 v3, 0xffff0000, v3
	v_or_b32_e32 v0, 4, v154
	v_lshlrev_b32_e32 v6, 16, v7
	v_and_b32_e32 v7, 0xffff0000, v7
	v_pk_mul_f32 v[14:15], v[10:11], v[2:3]
	v_cvt_f32_ubyte0_e32 v0, v0
	v_pk_fma_f32 v[14:15], v[12:13], v[6:7], v[14:15] neg_lo:[0,0,1] neg_hi:[0,0,1]
	v_mul_f32_e32 v0, 0xbd800000, v0
	v_pk_mul_f32 v[6:7], v[10:11], v[6:7]
	v_mul_f32_e32 v0, 0x41549a78, v0
	v_pk_fma_f32 v[2:3], v[12:13], v[2:3], v[6:7]
	v_exp_f32_e32 v0, v0
	v_cvt_pk_bf16_f32 v125, v2, v3
	v_or_b32_e32 v3, 5, v154
	v_cvt_f32_ubyte0_e32 v3, v3
	v_mul_f32_e32 v3, 0xbd800000, v3
	v_mul_f32_e32 v3, 0x41549a78, v3
	v_mul_f32_e32 v0, v0, v20
	v_exp_f32_e32 v3, v3
	v_mul_f32_e32 v2, 0.15915494, v0
	v_floor_f32_e32 v2, v2
	v_fma_f32 v0, v0, 0.15915494, -v2
	v_sin_f32_e32 v2, v0
	v_cos_f32_e32 v6, v0
	v_mul_f32_e32 v0, v3, v20
	v_mul_f32_e32 v3, 0.15915494, v0
	v_floor_f32_e32 v3, v3
	v_fma_f32 v0, v0, 0.15915494, -v3
	v_sin_f32_e32 v3, v0
	v_cos_f32_e32 v7, v0
	v_or_b32_e32 v0, 6, v154
	v_lshlrev_b32_e32 v10, 16, v8
	v_and_b32_e32 v11, 0xffff0000, v8
	v_lshlrev_b32_e32 v12, 16, v4
	v_and_b32_e32 v13, 0xffff0000, v4
	v_cvt_f32_ubyte0_e32 v0, v0
	v_cvt_pk_bf16_f32 v121, v14, v15
	v_pk_mul_f32 v[14:15], v[2:3], v[12:13]
	v_mul_f32_e32 v0, 0xbd800000, v0
	v_pk_mul_f32 v[2:3], v[2:3], v[10:11]
	v_mul_f32_e32 v0, 0x41549a78, v0
	v_pk_fma_f32 v[2:3], v[6:7], v[12:13], v[2:3]
	v_exp_f32_e32 v0, v0
	v_cvt_pk_bf16_f32 v126, v2, v3
	v_or_b32_e32 v3, 7, v154
	v_cvt_f32_ubyte0_e32 v3, v3
	v_mul_f32_e32 v3, 0xbd800000, v3
	v_mul_f32_e32 v3, 0x41549a78, v3
	v_mul_f32_e32 v0, v0, v20
	v_exp_f32_e32 v3, v3
	v_mul_f32_e32 v2, 0.15915494, v0
	v_floor_f32_e32 v2, v2
	v_fma_f32 v0, v0, 0.15915494, -v2
	v_pk_fma_f32 v[14:15], v[6:7], v[10:11], v[14:15] neg_lo:[0,0,1] neg_hi:[0,0,1]
	v_sin_f32_e32 v2, v0
	v_cos_f32_e32 v6, v0
	v_mul_f32_e32 v0, v3, v20
	v_mul_f32_e32 v3, 0.15915494, v0
	v_floor_f32_e32 v3, v3
	v_fma_f32 v0, v0, 0.15915494, -v3
	v_sin_f32_e32 v3, v0
	v_cos_f32_e32 v7, v0
	v_lshlrev_b32_e32 v8, 16, v9
	v_and_b32_e32 v9, 0xffff0000, v9
	v_lshlrev_b32_e32 v4, 16, v5
	v_and_b32_e32 v5, 0xffff0000, v5
	s_lshl_b32 s27, s64, 2
	s_ashr_i32 s26, s65, 7
	v_pk_mul_f32 v[10:11], v[2:3], v[4:5]
	v_pk_mul_f32 v[2:3], v[2:3], v[8:9]
	s_add_i32 s26, s26, s27
	v_pk_fma_f32 v[10:11], v[6:7], v[8:9], v[10:11] neg_lo:[0,0,1] neg_hi:[0,0,1]
	v_pk_fma_f32 v[2:3], v[6:7], v[4:5], v[2:3]
	v_cvt_pk_bf16_f32 v120, v18, v19
	v_cvt_pk_bf16_f32 v122, v14, v15
	v_cvt_pk_bf16_f32 v123, v10, v11
	s_cmp_ge_u32 s65, 0x100
	s_cbranch_scc0 .Lprio_skip
	s_setprio 1
.Lprio_skip:
	s_cmp_lt_i32 s26, 0
	v_cvt_pk_bf16_f32 v127, v2, v3
	s_cbranch_scc1 .LBB0_542
	ds_read_b128 v[2:5], v169
	ds_read_b128 v[6:9], v169 offset:32
	ds_read_b128 v[10:13], v169 offset:6656
	ds_read_b128 v[48:51], v169 offset:6688
	ds_read_b128 v[52:55], v169 offset:64
	ds_read_b128 v[56:59], v169 offset:96
	ds_read_b128 v[60:63], v169 offset:6720
	ds_read_b128 v[68:71], v169 offset:6752
	ds_read_b128 v[72:75], v169 offset:128
	ds_read_b128 v[76:79], v169 offset:160
	ds_read_b128 v[80:83], v169 offset:6784
	ds_read_b128 v[128:131], v169 offset:6816
	s_waitcnt lgkmcnt(11)
	v_mfma_f32_32x32x16_bf16 v[32:47], v[2:5], v[116:119], 0
	s_waitcnt lgkmcnt(9)
	v_mfma_f32_32x32x16_bf16 v[16:31], v[10:13], v[116:119], 0
	v_mfma_f32_32x32x16_bf16 v[32:47], v[6:9], v[112:115], v[32:47]
	s_waitcnt lgkmcnt(8)
	v_mfma_f32_32x32x16_bf16 v[16:31], v[48:51], v[112:115], v[16:31]
	s_waitcnt lgkmcnt(7)
	v_mfma_f32_32x32x16_bf16 v[32:47], v[52:55], v[108:111], v[32:47]
	s_waitcnt lgkmcnt(5)
	v_mfma_f32_32x32x16_bf16 v[16:31], v[60:63], v[108:111], v[16:31]
	v_mfma_f32_32x32x16_bf16 v[32:47], v[56:59], v[104:107], v[32:47]
	s_waitcnt lgkmcnt(4)
	v_mfma_f32_32x32x16_bf16 v[16:31], v[68:71], v[104:107], v[16:31]
	s_waitcnt lgkmcnt(3)
	v_mfma_f32_32x32x16_bf16 v[32:47], v[72:75], v[120:123], v[32:47]
	s_waitcnt lgkmcnt(1)
	v_mfma_f32_32x32x16_bf16 v[16:31], v[80:83], v[120:123], v[16:31]
	v_mfma_f32_32x32x16_bf16 v[32:47], v[76:79], v[124:127], v[32:47]
	s_waitcnt lgkmcnt(0)
	v_mfma_f32_32x32x16_bf16 v[16:31], v[128:131], v[124:127], v[16:31]
	v_add_u32_e32 v0, 0x6800, v165
	ds_read2_b64 v[128:131], v0 offset1:2
	ds_read2_b64 v[80:83], v0 offset0:4 offset1:6
	ds_read2_b64 v[76:79], v0 offset0:8 offset1:10
	ds_read2_b64 v[72:75], v0 offset0:12 offset1:14
	v_add_u32_e32 v0, 0x7800, v165
	ds_read2_b64 v[60:63], v0 offset0:32 offset1:34
	ds_read2_b64 v[50:53], v0 offset0:36 offset1:38
	ds_read2_b64 v[56:59], v0 offset0:40 offset1:42
	ds_read2_b64 v[68:71], v0 offset0:44 offset1:46
	s_nop 1
	v_max_f32_e32 v2, v17, v17
	v_max_f32_e32 v3, v16, v16
	v_max_f32_e32 v2, v3, v2
	v_max3_f32 v0, v32, v33, v34
	v_max3_f32 v2, v2, v18, v19
	v_max3_f32 v0, v0, v35, v36
	v_max3_f32 v2, v2, v20, v21
	v_max3_f32 v0, v0, v37, v38
	v_max3_f32 v2, v2, v22, v23
	v_max3_f32 v0, v0, v39, v40
	v_max3_f32 v2, v2, v24, v25
	v_max3_f32 v0, v0, v41, v42
	v_max3_f32 v2, v2, v26, v27
	v_max3_f32 v0, v0, v43, v44
	v_max3_f32 v2, v2, v28, v29
	v_max3_f32 v0, v0, v45, v46
	v_max3_f32 v2, v2, v30, v31
	v_max3_f32 v0, v0, v47, v2
	v_mov_b32_e32 v2, v0
	s_nop 1
	v_permlane32_swap_b32_e32 v0, v2
	v_max_f32_e32 v2, v2, v2
	v_max_f32_e32 v0, v0, v0
	v_max_f32_e32 v48, v0, v2
	v_sub_f32_e32 v0, v32, v48
	v_sub_f32_e32 v16, v16, v48
	v_sub_f32_e32 v32, v33, v48
	v_sub_f32_e32 v17, v17, v48
	v_exp_f32_e32 v49, v0
	v_exp_f32_e32 v93, v16
	v_exp_f32_e32 v32, v32
	v_exp_f32_e32 v0, v17
	v_sub_f32_e32 v34, v34, v48
	v_add_f32_e32 v33, v49, v93
	v_sub_f32_e32 v54, v18, v48
	v_pk_add_f32 v[16:17], v[32:33], v[0:1]
	v_sub_f32_e32 v35, v35, v48
	v_sub_f32_e32 v55, v19, v48
	v_pk_add_f32 v[18:19], v[16:17], v[16:17] op_sel_hi:[0,1]
	v_exp_f32_e32 v33, v34
	v_exp_f32_e32 v94, v54
	v_exp_f32_e32 v34, v35
	v_exp_f32_e32 v18, v55
	v_sub_f32_e32 v36, v36, v48
	v_add_f32_e32 v35, v33, v94
	v_sub_f32_e32 v54, v20, v48
	v_pk_add_f32 v[16:17], v[34:35], v[18:19]
	v_sub_f32_e32 v37, v37, v48
	v_sub_f32_e32 v55, v21, v48
	v_pk_add_f32 v[20:21], v[16:17], v[16:17] op_sel_hi:[0,1]
	v_exp_f32_e32 v19, v36
	v_exp_f32_e32 v35, v54
	v_exp_f32_e32 v36, v37
	v_exp_f32_e32 v20, v55
	v_sub_f32_e32 v38, v38, v48
	v_add_f32_e32 v37, v19, v35
	v_sub_f32_e32 v54, v22, v48
	v_pk_add_f32 v[16:17], v[36:37], v[20:21]
	v_sub_f32_e32 v39, v39, v48
	v_sub_f32_e32 v55, v23, v48
	v_pk_add_f32 v[22:23], v[16:17], v[16:17] op_sel_hi:[0,1]
	v_exp_f32_e32 v21, v38
	v_exp_f32_e32 v37, v54
	v_exp_f32_e32 v38, v39
	v_exp_f32_e32 v22, v55
	v_sub_f32_e32 v40, v40, v48
	v_add_f32_e32 v39, v21, v37
	v_sub_f32_e32 v54, v24, v48
	v_pk_add_f32 v[16:17], v[38:39], v[22:23]
	v_sub_f32_e32 v41, v41, v48
	v_sub_f32_e32 v55, v25, v48
	v_pk_add_f32 v[24:25], v[16:17], v[16:17] op_sel_hi:[0,1]
	v_exp_f32_e32 v23, v40
	v_exp_f32_e32 v39, v54
	v_exp_f32_e32 v40, v41
	v_exp_f32_e32 v24, v55
	v_sub_f32_e32 v42, v42, v48
	v_add_f32_e32 v41, v23, v39
	v_sub_f32_e32 v54, v26, v48
	v_pk_add_f32 v[16:17], v[40:41], v[24:25]
	v_sub_f32_e32 v43, v43, v48
	v_sub_f32_e32 v55, v27, v48
	v_pk_add_f32 v[26:27], v[16:17], v[16:17] op_sel_hi:[0,1]
	v_exp_f32_e32 v25, v42
	v_exp_f32_e32 v41, v54
	v_exp_f32_e32 v42, v43
	v_exp_f32_e32 v26, v55
	v_sub_f32_e32 v44, v44, v48
	v_add_f32_e32 v43, v25, v41
	v_sub_f32_e32 v54, v28, v48
	v_pk_add_f32 v[16:17], v[42:43], v[26:27]
	v_sub_f32_e32 v45, v45, v48
	v_sub_f32_e32 v55, v29, v48
	v_pk_add_f32 v[28:29], v[16:17], v[16:17] op_sel_hi:[0,1]
	v_exp_f32_e32 v27, v44
	v_exp_f32_e32 v43, v54
	v_exp_f32_e32 v44, v45
	v_exp_f32_e32 v28, v55
	v_sub_f32_e32 v46, v46, v48
	v_add_f32_e32 v45, v27, v43
	v_sub_f32_e32 v54, v30, v48
	v_pk_add_f32 v[16:17], v[44:45], v[28:29]
	v_sub_f32_e32 v47, v47, v48
	v_sub_f32_e32 v55, v31, v48
	v_pk_add_f32 v[30:31], v[16:17], v[16:17] op_sel_hi:[0,1]
	v_exp_f32_e32 v29, v46
	v_exp_f32_e32 v45, v54
	v_exp_f32_e64 v2, -v48
	v_exp_f32_e32 v46, v47
	v_exp_f32_e32 v30, v55
	v_add_f32_e32 v47, v29, v45
	v_mul_f32_e32 v2, 0, v2
	v_mov_b32_e32 v16, v2
	v_pk_add_f32 v[54:55], v[46:47], v[30:31]
	v_mov_b32_e32 v17, v2
	v_pk_add_f32 v[54:55], v[54:55], v[54:55] op_sel_hi:[0,1]
	v_mov_b32_e32 v3, v2
	v_mov_b32_e32 v4, v2
	v_mov_b32_e32 v5, v2
	v_mov_b32_e32 v6, v2
	v_mov_b32_e32 v7, v2
	v_mov_b32_e32 v8, v2
	v_mov_b32_e32 v9, v2
	v_mov_b32_e32 v10, v2
	v_mov_b32_e32 v11, v2
	v_mov_b32_e32 v12, v2
	v_mov_b32_e32 v13, v2
	v_mov_b32_e32 v14, v2
	v_mov_b32_e32 v15, v2
	v_cvt_pk_bf16_f32 v132, v49, v32
	v_cvt_pk_bf16_f32 v133, v33, v34
	v_cvt_pk_bf16_f32 v134, v19, v36
	v_cvt_pk_bf16_f32 v135, v21, v38
	v_cvt_pk_bf16_f32 v136, v23, v40
	v_cvt_pk_bf16_f32 v137, v25, v42
	v_cvt_pk_bf16_f32 v138, v27, v44
	v_cvt_pk_bf16_f32 v139, v29, v46
	v_cvt_pk_bf16_f32 v140, v93, v0
	v_cvt_pk_bf16_f32 v141, v94, v18
	v_cvt_pk_bf16_f32 v142, v35, v20
	v_cvt_pk_bf16_f32 v143, v37, v22
	v_cvt_pk_bf16_f32 v144, v39, v24
	v_cvt_pk_bf16_f32 v145, v41, v26
	v_cvt_pk_bf16_f32 v146, v43, v28
	v_cvt_pk_bf16_f32 v147, v45, v30
	s_waitcnt lgkmcnt(0)
	v_mfma_f32_32x32x16_bf16 v[32:47], v[128:131], v[132:135], v[2:17]
	v_mov_b64_e32 v[30:31], v[16:17]
	v_mov_b64_e32 v[28:29], v[14:15]
	v_mov_b64_e32 v[26:27], v[12:13]
	v_mov_b64_e32 v[24:25], v[10:11]
	v_mov_b64_e32 v[22:23], v[8:9]
	v_mov_b64_e32 v[20:21], v[6:7]
	v_mov_b64_e32 v[18:19], v[4:5]
	v_mov_b64_e32 v[16:17], v[2:3]
	v_mfma_f32_32x32x16_bf16 v[32:47], v[80:83], v[136:139], v[32:47]
	v_mov_b32_e32 v49, v2
	v_mov_b32_e32 v54, v1
	v_add_f32_e64 v158, v48, v54
	v_add_f32_e64 v159, v49, v55
	v_xor_b32_e32 v48, 0x80000000, v158
	v_mov_b32_e32 v49, v48
	v_mov_b32_e32 v54, v48
	v_mfma_f32_32x32x16_bf16 v[16:31], v[60:63], v[132:135], v[16:31]
	v_mov_b32_e32 v55, v48
	v_mov_b32_e32 v60, v48
	v_mov_b32_e32 v61, v48
	v_mov_b32_e32 v62, v48
	v_mov_b32_e32 v63, v48
	v_mfma_f32_32x32x16_bf16 v[16:31], v[50:53], v[136:139], v[16:31]
	v_mov_b32_e32 v50, v48
	v_mov_b32_e32 v51, v48
	v_mov_b32_e32 v52, v48
	v_mov_b32_e32 v53, v48
	v_mfma_f32_32x32x16_bf16 v[32:47], v[76:79], v[140:143], v[32:47]
	v_mfma_f32_32x32x16_bf16 v[16:31], v[56:59], v[140:143], v[16:31]
	v_mov_b32_e32 v56, v48
	v_mov_b32_e32 v57, v48
	v_mov_b32_e32 v58, v48
	v_mov_b32_e32 v59, v48
	v_mfma_f32_32x32x16_bf16 v[32:47], v[72:75], v[144:147], v[32:47]
	v_mfma_f32_32x32x16_bf16 v[16:31], v[68:71], v[144:147], v[16:31]
	s_and_saveexec_b64 s[6:7], s[2:3]
	s_cbranch_execnz .LBB0_543
	s_branch .LBB0_544
